# in-proj epilogue without per-row-group store round trips: rstd loads up front, address/temporary registers moved off pending store data, one padded vmcnt(0) after the last store
# baseline (speedup 1.0000x reference)
;     __device__ __forceinline__ void operator()(const f32x4 (&acc)[2][2][4][2], const Unit& u, int wr, int wc, int fr, int fq) const {
;         const int row0 = u.pm * BM + wr * 64 + fr, col0 = u.pn * BM + wc * 32 + 8 * fq;
; #pragma unroll
;         for (int ai = 0; ai < 2; ++ai)
; #pragma unroll
;             for (int m = 0; m < 4; ++m) {
;                 const int row = row0 + ai * HALF + m * 16; const float s = rs[row]; bf16_t* rowp = O + (size_t)row * ldc + col0;
; #pragma unroll
;                 for (int bj = 0; bj < 2; ++bj) { const f32x4 v0 = acc[ai][bj][m][0] * s, v1 = acc[ai][bj][m][1] * s; u32x4 w;
;                     w.x = pk2(v0[0], v0[1]); w.y = pk2(v0[2], v0[3]); w.z = pk2(v1[0], v1[1]); w.w = pk2(v1[2], v1[3]); *(u32x4*)(rowp + bj * HALF) = w; }
.LBB0_165:
	v_lshl_add_u32 v146, s51, 8, v148
	v_ashrrev_i32_e32 v147, 31, v146
	v_lshl_add_u64 v[142:143], v[146:147], 2, s[14:15]
	global_load_dword v152, v[142:143], off
	global_load_dword v196, v[142:143], off offset:64
	global_load_dword v200, v[142:143], off offset:128
	global_load_dword v204, v[142:143], off offset:192
	global_load_dword v232, v[142:143], off offset:512
	global_load_dword v234, v[142:143], off offset:576
	global_load_dword v236, v[142:143], off offset:640
	global_load_dword v238, v[142:143], off offset:704
	v_lshl_or_b32 v140, s50, 8, v150
	v_ashrrev_i32_e32 v141, 31, v140
	v_lshlrev_b64 v[144:145], 12, v[146:147]
	v_lshl_add_u64 v[154:155], s[10:11], 0, v[144:145]
	v_lshlrev_b64 v[144:145], 1, v[140:141]
	v_lshl_add_u64 v[140:141], v[154:155], 0, v[144:145]
	s_mov_b32 s19, 0x80000
	s_mov_b64 s[26:27], 0x80000
	s_mov_b32 s60, 0x2dc0000
	s_waitcnt vmcnt(0)
	v_pk_mul_f32 v[128:129], v[128:129], v[152:153] op_sel_hi:[1,0]
	v_pk_mul_f32 v[126:127], v[126:127], v[152:153] op_sel_hi:[1,0]
	v_pk_mul_f32 v[154:155], v[124:125], v[152:153] op_sel_hi:[1,0]
	v_pk_mul_f32 v[124:125], v[122:123], v[152:153] op_sel_hi:[1,0]
	v_cvt_pk_bf16_f32 v122, v126, v127
	v_cvt_pk_bf16_f32 v123, v128, v129
	v_cvt_pk_bf16_f32 v124, v124, v125
	v_cvt_pk_bf16_f32 v125, v154, v155
	global_store_dwordx4 v[140:141], v[122:125], off
	v_pk_mul_f32 v[120:121], v[120:121], v[152:153] op_sel_hi:[1,0]
	v_pk_mul_f32 v[118:119], v[118:119], v[152:153] op_sel_hi:[1,0]
	v_pk_mul_f32 v[190:191], v[116:117], v[152:153] op_sel_hi:[1,0]
	v_pk_mul_f32 v[116:117], v[114:115], v[152:153] op_sel_hi:[1,0]
	v_cvt_pk_bf16_f32 v114, v118, v119
	v_cvt_pk_bf16_f32 v115, v120, v121
	v_cvt_pk_bf16_f32 v116, v116, v117
	v_cvt_pk_bf16_f32 v117, v190, v191
	global_store_dwordx4 v[140:141], v[114:117], off offset:256
	s_nop 1
	v_or_b32_e32 v176, 16, v146
	v_ashrrev_i32_e32 v177, 31, v176
	v_lshlrev_b64 v[176:177], 12, v[176:177]
	v_lshl_add_u64 v[176:177], s[10:11], 0, v[176:177]
	v_lshl_add_u64 v[176:177], v[176:177], 0, v[144:145]
	v_pk_mul_f32 v[112:113], v[112:113], v[196:197] op_sel_hi:[1,0]
	v_pk_mul_f32 v[110:111], v[110:111], v[196:197] op_sel_hi:[1,0]
	v_pk_mul_f32 v[118:119], v[108:109], v[196:197] op_sel_hi:[1,0]
	v_pk_mul_f32 v[108:109], v[106:107], v[196:197] op_sel_hi:[1,0]
	v_cvt_pk_bf16_f32 v106, v110, v111
	v_cvt_pk_bf16_f32 v107, v112, v113
	v_cvt_pk_bf16_f32 v108, v108, v109
	v_cvt_pk_bf16_f32 v109, v118, v119
	global_store_dwordx4 v[176:177], v[106:109], off
	v_pk_mul_f32 v[104:105], v[104:105], v[196:197] op_sel_hi:[1,0]
	v_pk_mul_f32 v[102:103], v[102:103], v[196:197] op_sel_hi:[1,0]
	v_pk_mul_f32 v[192:193], v[100:101], v[196:197] op_sel_hi:[1,0]
	v_pk_mul_f32 v[100:101], v[98:99], v[196:197] op_sel_hi:[1,0]
	v_cvt_pk_bf16_f32 v98, v102, v103
	v_cvt_pk_bf16_f32 v99, v104, v105
	v_cvt_pk_bf16_f32 v100, v100, v101
	v_cvt_pk_bf16_f32 v101, v192, v193
	global_store_dwordx4 v[176:177], v[98:101], off offset:256
	s_nop 1
	v_or_b32_e32 v178, 32, v146
	v_ashrrev_i32_e32 v179, 31, v178
	v_lshlrev_b64 v[178:179], 12, v[178:179]
	v_lshl_add_u64 v[178:179], s[10:11], 0, v[178:179]
	v_lshl_add_u64 v[178:179], v[178:179], 0, v[144:145]
	v_pk_mul_f32 v[96:97], v[96:97], v[200:201] op_sel_hi:[1,0]
	v_pk_mul_f32 v[94:95], v[94:95], v[200:201] op_sel_hi:[1,0]
	v_pk_mul_f32 v[102:103], v[92:93], v[200:201] op_sel_hi:[1,0]
	v_pk_mul_f32 v[92:93], v[90:91], v[200:201] op_sel_hi:[1,0]
	v_cvt_pk_bf16_f32 v90, v94, v95
	v_cvt_pk_bf16_f32 v91, v96, v97
	v_cvt_pk_bf16_f32 v92, v92, v93
	v_cvt_pk_bf16_f32 v93, v102, v103
	global_store_dwordx4 v[178:179], v[90:93], off
	v_pk_mul_f32 v[88:89], v[88:89], v[200:201] op_sel_hi:[1,0]
	v_pk_mul_f32 v[86:87], v[86:87], v[200:201] op_sel_hi:[1,0]
	v_pk_mul_f32 v[194:195], v[84:85], v[200:201] op_sel_hi:[1,0]
	v_pk_mul_f32 v[84:85], v[82:83], v[200:201] op_sel_hi:[1,0]
	v_cvt_pk_bf16_f32 v82, v86, v87
	v_cvt_pk_bf16_f32 v83, v88, v89
	v_cvt_pk_bf16_f32 v84, v84, v85
	v_cvt_pk_bf16_f32 v85, v194, v195
	global_store_dwordx4 v[178:179], v[82:85], off offset:256
	s_nop 1
	v_or_b32_e32 v180, 48, v146
	v_ashrrev_i32_e32 v181, 31, v180
	v_lshlrev_b64 v[180:181], 12, v[180:181]
	v_lshl_add_u64 v[180:181], s[10:11], 0, v[180:181]
	v_lshl_add_u64 v[180:181], v[180:181], 0, v[144:145]
	v_pk_mul_f32 v[80:81], v[80:81], v[204:205] op_sel_hi:[1,0]
	v_pk_mul_f32 v[78:79], v[78:79], v[204:205] op_sel_hi:[1,0]
	v_pk_mul_f32 v[86:87], v[76:77], v[204:205] op_sel_hi:[1,0]
	v_pk_mul_f32 v[76:77], v[74:75], v[204:205] op_sel_hi:[1,0]
	v_cvt_pk_bf16_f32 v74, v78, v79
	v_cvt_pk_bf16_f32 v75, v80, v81
	v_cvt_pk_bf16_f32 v76, v76, v77
	v_cvt_pk_bf16_f32 v77, v86, v87
	global_store_dwordx4 v[180:181], v[74:77], off
	v_pk_mul_f32 v[72:73], v[72:73], v[204:205] op_sel_hi:[1,0]
; #define PG8_BAR __builtin_amdgcn_s_barrier()
;     __device__ __forceinline__ void operator()(const f32x4 (&acc)[2][2][4][2], const Unit& u, int wr, int wc, int fr, int fq) const {
;     ...
;             for (int m = 0; m < 4; ++m) {
;                 const int row = row0 + ai * HALF + m * 16; const float s = rs[row]; bf16_t* rowp = O + (size_t)row * ldc + col0;
; #pragma unroll
;                 for (int bj = 0; bj < 2; ++bj) { const f32x4 v0 = acc[ai][bj][m][0] * s, v1 = acc[ai][bj][m][1] * s; u32x4 w;
;                     w.x = pk2(v0[0], v0[1]); w.y = pk2(v0[2], v0[3]); w.z = pk2(v1[0], v1[1]); w.w = pk2(v1[2], v1[3]); *(u32x4*)(rowp + bj * HALF) = w; }
; template <class Epi, bool UPMODE>
; __device__ __forceinline__ void gemm_phase(LAS unsigned char* lds, const Gemm g, const StaticOrder& S, const Epi& E) {
;     ...
;         if (!has_next) break;
; #pragma unroll
;         for (int a = 0; a < 2; ++a)
; #pragma unroll
;             for (int b = 0; b < 2; ++b)
; #pragma unroll
;                 for (int m = 0; m < 4; ++m)
; #pragma unroll
;                     for (int n = 0; n < 2; ++n) acc[a][b][m][n] = (f32x4){0.f, 0.f, 0.f, 0.f};
;         cur = nxt; cA = nA; cB = nB; ++ui;
;         if (wr == 1) PG8_BAR;
	v_pk_mul_f32 v[70:71], v[70:71], v[204:205] op_sel_hi:[1,0]
	v_pk_mul_f32 v[198:199], v[68:69], v[204:205] op_sel_hi:[1,0]
	v_pk_mul_f32 v[68:69], v[66:67], v[204:205] op_sel_hi:[1,0]
	v_cvt_pk_bf16_f32 v66, v70, v71
	v_cvt_pk_bf16_f32 v67, v72, v73
	v_cvt_pk_bf16_f32 v68, v68, v69
	v_cvt_pk_bf16_f32 v69, v198, v199
	global_store_dwordx4 v[180:181], v[66:69], off offset:256
	v_pk_mul_f32 v[62:63], v[62:63], v[232:233] op_sel_hi:[1,0]
	v_pk_mul_f32 v[64:65], v[64:65], v[232:233] op_sel_hi:[1,0]
	v_pk_mul_f32 v[70:71], v[60:61], v[232:233] op_sel_hi:[1,0]
	v_pk_mul_f32 v[60:61], v[58:59], v[232:233] op_sel_hi:[1,0]
	v_cvt_pk_bf16_f32 v58, v62, v63
	v_add_co_u32_e32 v62, vcc, s19, v140
	v_cvt_pk_bf16_f32 v59, v64, v65
	v_cvt_pk_bf16_f32 v60, v60, v61
	v_cvt_pk_bf16_f32 v61, v70, v71
	v_addc_co_u32_e32 v63, vcc, 0, v141, vcc
	global_store_dwordx4 v[62:63], v[58:61], off
	v_pk_mul_f32 v[56:57], v[56:57], v[232:233] op_sel_hi:[1,0]
	v_pk_mul_f32 v[54:55], v[54:55], v[232:233] op_sel_hi:[1,0]
	v_pk_mul_f32 v[202:203], v[52:53], v[232:233] op_sel_hi:[1,0]
	v_pk_mul_f32 v[52:53], v[50:51], v[232:233] op_sel_hi:[1,0]
	v_lshl_add_u64 v[182:183], v[140:141], 0, s[26:27]
	v_cvt_pk_bf16_f32 v50, v54, v55
	v_cvt_pk_bf16_f32 v51, v56, v57
	v_cvt_pk_bf16_f32 v52, v52, v53
	v_cvt_pk_bf16_f32 v53, v202, v203
	global_store_dwordx4 v[182:183], v[50:53], off offset:256
	s_mov_b32 s19, 0x90000
	s_mov_b64 s[26:27], 0x90000
	v_lshl_add_u64 v[184:185], v[140:141], 0, s[26:27]
	s_mov_b64 s[26:27], 0xa0000
	v_pk_mul_f32 v[46:47], v[46:47], v[234:235] op_sel_hi:[1,0]
	v_pk_mul_f32 v[48:49], v[48:49], v[234:235] op_sel_hi:[1,0]
	v_pk_mul_f32 v[54:55], v[44:45], v[234:235] op_sel_hi:[1,0]
	v_pk_mul_f32 v[44:45], v[42:43], v[234:235] op_sel_hi:[1,0]
	v_cvt_pk_bf16_f32 v42, v46, v47
	v_add_co_u32_e32 v46, vcc, s19, v140
	v_cvt_pk_bf16_f32 v43, v48, v49
	v_cvt_pk_bf16_f32 v44, v44, v45
	v_cvt_pk_bf16_f32 v45, v54, v55
	v_addc_co_u32_e32 v47, vcc, 0, v141, vcc
	global_store_dwordx4 v[46:47], v[42:45], off
	v_pk_mul_f32 v[40:41], v[40:41], v[234:235] op_sel_hi:[1,0]
	v_pk_mul_f32 v[38:39], v[38:39], v[234:235] op_sel_hi:[1,0]
	v_pk_mul_f32 v[206:207], v[36:37], v[234:235] op_sel_hi:[1,0]
	v_pk_mul_f32 v[36:37], v[34:35], v[234:235] op_sel_hi:[1,0]
	v_cvt_pk_bf16_f32 v34, v38, v39
	v_cvt_pk_bf16_f32 v35, v40, v41
	v_cvt_pk_bf16_f32 v36, v36, v37
	v_cvt_pk_bf16_f32 v37, v206, v207
	global_store_dwordx4 v[184:185], v[34:37], off offset:256
	s_mov_b32 s19, 0xa0000
	v_lshl_add_u64 v[186:187], v[140:141], 0, s[26:27]
	s_mov_b64 s[26:27], 0xb0000
	v_pk_mul_f32 v[30:31], v[30:31], v[236:237] op_sel_hi:[1,0]
	v_pk_mul_f32 v[32:33], v[32:33], v[236:237] op_sel_hi:[1,0]
	v_pk_mul_f32 v[38:39], v[28:29], v[236:237] op_sel_hi:[1,0]
	v_pk_mul_f32 v[28:29], v[26:27], v[236:237] op_sel_hi:[1,0]
	v_cvt_pk_bf16_f32 v26, v30, v31
	v_add_co_u32_e32 v30, vcc, s19, v140
	v_cvt_pk_bf16_f32 v27, v32, v33
	v_cvt_pk_bf16_f32 v28, v28, v29
	v_cvt_pk_bf16_f32 v29, v38, v39
	v_addc_co_u32_e32 v31, vcc, 0, v141, vcc
	global_store_dwordx4 v[30:31], v[26:29], off
	v_pk_mul_f32 v[24:25], v[24:25], v[236:237] op_sel_hi:[1,0]
	v_pk_mul_f32 v[22:23], v[22:23], v[236:237] op_sel_hi:[1,0]
	v_pk_mul_f32 v[208:209], v[20:21], v[236:237] op_sel_hi:[1,0]
	v_pk_mul_f32 v[20:21], v[18:19], v[236:237] op_sel_hi:[1,0]
	v_cvt_pk_bf16_f32 v18, v22, v23
	v_cvt_pk_bf16_f32 v19, v24, v25
	v_cvt_pk_bf16_f32 v20, v20, v21
	v_cvt_pk_bf16_f32 v21, v208, v209
	global_store_dwordx4 v[186:187], v[18:21], off offset:256
	s_mov_b32 s19, 0xb0000
	v_lshl_add_u64 v[188:189], v[140:141], 0, s[26:27]
	s_mov_b64 s[26:27], -1
	v_pk_mul_f32 v[14:15], v[14:15], v[238:239] op_sel_hi:[1,0]
	v_pk_mul_f32 v[16:17], v[16:17], v[238:239] op_sel_hi:[1,0]
	v_pk_mul_f32 v[22:23], v[12:13], v[238:239] op_sel_hi:[1,0]
	v_pk_mul_f32 v[12:13], v[10:11], v[238:239] op_sel_hi:[1,0]
	v_cvt_pk_bf16_f32 v10, v14, v15
	v_add_co_u32_e32 v14, vcc, s19, v140
	v_cvt_pk_bf16_f32 v11, v16, v17
	v_cvt_pk_bf16_f32 v12, v12, v13
	v_cvt_pk_bf16_f32 v13, v22, v23
	v_addc_co_u32_e32 v15, vcc, 0, v141, vcc
	global_store_dwordx4 v[14:15], v[10:13], off
	v_pk_mul_f32 v[8:9], v[8:9], v[238:239] op_sel_hi:[1,0]
	v_pk_mul_f32 v[6:7], v[6:7], v[238:239] op_sel_hi:[1,0]
	v_pk_mul_f32 v[210:211], v[4:5], v[238:239] op_sel_hi:[1,0]
	v_pk_mul_f32 v[4:5], v[2:3], v[238:239] op_sel_hi:[1,0]
	v_cvt_pk_bf16_f32 v2, v6, v7
	v_cvt_pk_bf16_f32 v3, v8, v9
	v_cvt_pk_bf16_f32 v4, v4, v5
	v_cvt_pk_bf16_f32 v5, v210, v211
	s_andn2_b64 vcc, exec, s[6:7]
	global_store_dwordx4 v[188:189], v[2:5], off offset:256
	s_nop 1
	s_waitcnt vmcnt(0)
	s_cbranch_vccnz .LBB0_154
	s_andn2_b64 vcc, exec, s[8:9]
	s_cbranch_vccnz .LBB0_153
	s_barrier
	s_branch .LBB0_153
